# attention unit start: line-touch loads for the first key tile of the selected pass and the first two tiles of the sliding-window pass
# speedup vs baseline: 1.0137x; 1.0137x over previous
.LBB0_944:
	s_bfe_u32 s0, s94, 0x40004
	s_xor_b32 s1, s0, 31
	s_cmpk_lt_i32 s94, 0x100
	s_cselect_b32 s22, s1, s0
	s_bfe_u32 s23, s94, 0x30001
	s_and_b32 s24, s94, 1
	v_readlane_b32 s0, v254, 15
	v_readlane_b32 s1, v254, 17
	s_mul_i32 s2, s23, 0x300000
	s_add_u32 s0, s0, s2
	s_addc_u32 s1, s1, 0
	s_lshl_b32 s2, s24, 7
	s_add_u32 s0, s0, s2
	s_addc_u32 s1, s1, 0
	v_mul_u32_u24_e32 v252, 0x600, v202
	v_mov_b32_e32 v253, 0
	v_lshl_add_u64 v[252:253], s[0:1], 0, v[252:253]
	global_load_dword v207, v[252:253], off offset:512
	global_load_dword v207, v[252:253], off offset:768
	s_sub_i32 s2, s22, 8
	s_max_i32 s2, s2, 0
	s_mul_i32 s2, s2, 0x18000
	v_mov_b32_e32 v250, s2
	v_mov_b32_e32 v251, 0
	v_lshl_add_u64 v[252:253], v[252:253], 0, v[250:251]
	global_load_dword v207, v[252:253], off offset:1024
	global_load_dword v207, v[252:253], off offset:1280
	v_mov_b32_e32 v250, 0x18000
	v_lshl_add_u64 v[252:253], v[252:253], 0, v[250:251]
	global_load_dword v207, v[252:253], off offset:1024
	global_load_dword v207, v[252:253], off offset:1280
	s_lshl_b32 s1, s24, 14
	s_lshl_b32 s2, s23, 15
	s_or_b32 s2, s2, s1
	v_lshl_add_u64 v[6:7], v[112:113], 0, s[2:3]
	v_lshl_add_u64 v[2:3], v[6:7], 0, v[124:125]
	global_load_dwordx4 v[96:99], v[2:3], off
	v_lshl_add_u64 v[8:9], v[114:115], 0, s[2:3]
	v_lshl_add_u64 v[2:3], v[8:9], 0, v[124:125]
	global_load_dwordx4 v[100:103], v[2:3], off
	v_lshl_add_u64 v[2:3], v[6:7], 0, v[126:127]
	global_load_dwordx4 v[104:107], v[2:3], off
	v_lshl_add_u64 v[2:3], v[8:9], 0, v[126:127]
	global_load_dwordx4 v[108:111], v[2:3], off
	v_add_u32_e32 v0, v123, v134
	s_lshl_b32 s0, s24, 2
	v_lshl_or_b32 v243, s22, 6, v232
	s_add_i32 s2, s0, s96
	v_lshl_or_b32 v244, s23, 11, v243
	v_lshlrev_b32_e32 v128, 10, v244
	v_mov_b32_e32 v129, v1
	s_lshl_b32 s88, s2, 6
	s_ashr_i32 s89, s88, 31
	s_mov_b32 s0, 0xf149f2ca
	v_lshl_add_u64 v[2:3], s[82:83], 0, v[128:129]
	v_lshl_add_u64 v[2:3], s[88:89], 1, v[2:3]
	v_lshl_add_u64 v[2:3], v[116:117], 1, v[2:3]
	global_load_dwordx4 v[80:83], v[2:3], off
	global_load_dwordx4 v[84:87], v[2:3], off offset:32
	global_load_dwordx4 v[88:91], v[2:3], off offset:64
	global_load_dwordx4 v[92:95], v[2:3], off offset:96
	s_waitcnt vmcnt(7)
	ds_write_b128 v0, v[96:99] offset:21504
	s_nop 0
	v_add_u32_e32 v0, v123, v135
	s_waitcnt vmcnt(6)
	ds_write_b128 v0, v[100:103] offset:39936
	s_nop 0
	v_subrev_u32_e32 v0, 31, v243
	v_ashrrev_i32_e32 v0, 4, v0
	v_cmp_le_i32_e32 vcc, v118, v0
	s_waitcnt vmcnt(5)
	ds_write_b128 v233, v[104:107] offset:21504
	s_waitcnt vmcnt(4)
	ds_write_b128 v234, v[108:111] offset:39936
	s_waitcnt lgkmcnt(0)
	s_barrier
	ds_read_b128 v[66:69], v235 offset:21504
	ds_read_b128 v[70:73], v235 offset:21536
	ds_read_b128 v[74:77], v235 offset:21568
	ds_read_b128 v[96:99], v235 offset:21600
	ds_read_b128 v[100:103], v235 offset:26112
	ds_read_b128 v[104:107], v235 offset:26144
	s_waitcnt vmcnt(3)
	s_waitcnt lgkmcnt(5)
	v_mfma_f32_32x32x16_bf16 v[50:65], v[66:69], v[80:83], 0
	ds_read_b128 v[66:69], v235 offset:26176
	s_waitcnt vmcnt(2)
	s_waitcnt lgkmcnt(5)
	v_mfma_f32_32x32x16_bf16 v[50:65], v[70:73], v[84:87], v[50:65]
	ds_read_b128 v[70:73], v235 offset:26208
	s_waitcnt vmcnt(1)
	s_waitcnt lgkmcnt(5)
	v_mfma_f32_32x32x16_bf16 v[50:65], v[74:77], v[88:91], v[50:65]
	ds_read_b128 v[74:77], v235 offset:30720
	s_waitcnt vmcnt(0)
	s_waitcnt lgkmcnt(5)
	v_mfma_f32_32x32x16_bf16 v[50:65], v[96:99], v[92:95], v[50:65]
	ds_read_b128 v[96:99], v235 offset:30752
	s_waitcnt lgkmcnt(5)
	v_mfma_f32_32x32x16_bf16 v[34:49], v[100:103], v[80:83], 0
	ds_read_b128 v[100:103], v235 offset:30784
	s_nop 7
	v_cndmask_b32_e32 v50, v236, v50, vcc
	v_cmp_lt_i32_e32 vcc, v118, v0
	s_nop 1
	v_cndmask_b32_e32 v51, v236, v51, vcc
	v_cmp_le_i32_e32 vcc, v137, v0
	s_waitcnt lgkmcnt(5)
	v_mfma_f32_32x32x16_bf16 v[34:49], v[104:107], v[84:87], v[34:49]
	ds_read_b128 v[104:107], v235 offset:30816
	v_cndmask_b32_e32 v52, v236, v52, vcc
	v_cmp_le_i32_e32 vcc, v138, v0
	s_nop 1
	v_cndmask_b32_e32 v53, v236, v53, vcc
	v_cmp_le_i32_e32 vcc, v139, v0
	s_waitcnt lgkmcnt(5)
	v_mfma_f32_32x32x16_bf16 v[34:49], v[66:69], v[88:91], v[34:49]
	ds_read_b128 v[66:69], v235 offset:35328
	v_cndmask_b32_e32 v54, v236, v54, vcc
	v_cmp_le_i32_e32 vcc, v140, v0
	s_nop 1
	v_cndmask_b32_e32 v55, v236, v55, vcc
	v_cmp_le_i32_e32 vcc, v141, v0
	s_waitcnt lgkmcnt(5)
	v_mfma_f32_32x32x16_bf16 v[34:49], v[70:73], v[92:95], v[34:49]
	ds_read_b128 v[70:73], v235 offset:35360
	s_waitcnt lgkmcnt(5)
	v_mfma_f32_32x32x16_bf16 v[18:33], v[74:77], v[80:83], 0
	ds_read_b128 v[74:77], v235 offset:35392
	s_waitcnt lgkmcnt(5)
	v_mfma_f32_32x32x16_bf16 v[18:33], v[96:99], v[84:87], v[18:33]
	ds_read_b128 v[96:99], v235 offset:35424
	s_waitcnt lgkmcnt(5)
	v_mfma_f32_32x32x16_bf16 v[18:33], v[100:103], v[88:91], v[18:33]
	s_waitcnt lgkmcnt(4)
	v_mfma_f32_32x32x16_bf16 v[18:33], v[104:107], v[92:95], v[18:33]
	s_waitcnt lgkmcnt(3)
	v_mfma_f32_32x32x16_bf16 v[2:17], v[66:69], v[80:83], 0
	s_waitcnt lgkmcnt(2)
	v_mfma_f32_32x32x16_bf16 v[2:17], v[70:73], v[84:87], v[2:17]
	s_waitcnt lgkmcnt(1)
	v_mfma_f32_32x32x16_bf16 v[2:17], v[74:77], v[88:91], v[2:17]
	s_waitcnt lgkmcnt(0)
	v_mfma_f32_32x32x16_bf16 v[2:17], v[96:99], v[92:95], v[2:17]
	v_max3_f32 v66, v50, s0, v51
	v_max3_f32 v66, v66, v52, v53
	v_cndmask_b32_e32 v67, v236, v56, vcc
	v_cmp_le_i32_e32 vcc, v142, v0
	v_max3_f32 v66, v66, v54, v55
	s_nop 0
	v_cndmask_b32_e32 v68, v236, v57, vcc
	v_cmp_le_i32_e32 vcc, v143, v0
	v_max3_f32 v56, v66, v67, v68
	s_nop 0
	v_cndmask_b32_e32 v66, v236, v58, vcc
	v_cmp_le_i32_e32 vcc, v144, v0
	s_nop 1
	v_cndmask_b32_e32 v69, v236, v59, vcc
	v_cmp_le_i32_e32 vcc, v145, v0
	v_max3_f32 v56, v56, v66, v69
	s_nop 0
	v_cndmask_b32_e32 v70, v236, v60, vcc
	v_cmp_le_i32_e32 vcc, v146, v0
	s_nop 1
	v_cndmask_b32_e32 v71, v236, v61, vcc
	v_cmp_le_i32_e32 vcc, v147, v0
	v_max3_f32 v56, v56, v70, v71
	s_nop 0
	v_cndmask_b32_e32 v72, v236, v62, vcc
	v_cmp_le_i32_e32 vcc, v148, v0
	s_nop 1
	v_cndmask_b32_e32 v73, v236, v63, vcc
	v_cmp_le_i32_e32 vcc, v149, v0
	v_max3_f32 v56, v56, v72, v73
	s_nop 0
	v_cndmask_b32_e32 v74, v236, v64, vcc
	v_cmp_le_i32_e32 vcc, v150, v0
	s_nop 1
	v_cndmask_b32_e32 v75, v236, v65, vcc
	v_cmp_le_i32_e32 vcc, v151, v0
	v_max3_f32 v56, v56, v74, v75
	s_nop 0
	v_cndmask_b32_e32 v34, v236, v34, vcc
	v_cmp_lt_i32_e32 vcc, v151, v0
	s_nop 1
	v_cndmask_b32_e32 v35, v236, v35, vcc
	v_cmp_le_i32_e32 vcc, v152, v0
	v_max3_f32 v56, v56, v34, v35
	s_nop 0
	v_cndmask_b32_e32 v36, v236, v36, vcc
	v_cmp_le_i32_e32 vcc, v153, v0
	s_nop 1
	v_cndmask_b32_e32 v37, v236, v37, vcc
	v_cmp_le_i32_e32 vcc, v154, v0
	v_max3_f32 v56, v56, v36, v37
	s_nop 0
	v_cndmask_b32_e32 v38, v236, v38, vcc
	v_cmp_le_i32_e32 vcc, v155, v0
	s_nop 1
	v_cndmask_b32_e32 v39, v236, v39, vcc
	v_cmp_le_i32_e32 vcc, v156, v0
	v_max3_f32 v56, v56, v38, v39
	s_nop 0
	v_cndmask_b32_e32 v40, v236, v40, vcc
	v_cmp_le_i32_e32 vcc, v157, v0
	s_nop 1
	v_cndmask_b32_e32 v41, v236, v41, vcc
	v_cmp_le_i32_e32 vcc, v158, v0
	v_max3_f32 v56, v56, v40, v41
	s_nop 0
	v_cndmask_b32_e32 v42, v236, v42, vcc
	v_cmp_le_i32_e32 vcc, v159, v0
	s_nop 1
	v_cndmask_b32_e32 v43, v236, v43, vcc
	v_cmp_le_i32_e32 vcc, v160, v0
	v_max3_f32 v56, v56, v42, v43
	s_nop 0
	v_cndmask_b32_e32 v44, v236, v44, vcc
	v_cmp_le_i32_e32 vcc, v161, v0
	s_nop 1
	v_cndmask_b32_e32 v45, v236, v45, vcc
	v_cmp_le_i32_e32 vcc, v162, v0
	v_max3_f32 v56, v56, v44, v45
	s_nop 0
	v_cndmask_b32_e32 v46, v236, v46, vcc
	v_cmp_le_i32_e32 vcc, v163, v0
	s_nop 1
	v_cndmask_b32_e32 v47, v236, v47, vcc
	v_cmp_le_i32_e32 vcc, v164, v0
	v_max3_f32 v56, v56, v46, v47
	s_nop 0
	v_cndmask_b32_e32 v48, v236, v48, vcc
	v_cmp_le_i32_e32 vcc, v165, v0
	s_nop 1
	v_cndmask_b32_e32 v49, v236, v49, vcc
	v_cmp_le_i32_e32 vcc, v166, v0
	v_max3_f32 v56, v56, v48, v49
	s_nop 0
	v_cndmask_b32_e32 v76, v236, v18, vcc
	v_cmp_lt_i32_e32 vcc, v166, v0
	s_nop 1
	v_cndmask_b32_e32 v77, v236, v19, vcc
	v_cmp_le_i32_e32 vcc, v167, v0
	v_max3_f32 v18, v56, v76, v77
	s_nop 0
	v_cndmask_b32_e32 v78, v236, v20, vcc
	v_cmp_le_i32_e32 vcc, v168, v0
	s_nop 1
	v_cndmask_b32_e32 v79, v236, v21, vcc
	v_cmp_le_i32_e32 vcc, v169, v0
	v_max3_f32 v18, v18, v78, v79
	s_nop 0
	v_cndmask_b32_e32 v96, v236, v22, vcc
	v_cmp_le_i32_e32 vcc, v170, v0
	s_nop 1
	v_cndmask_b32_e32 v97, v236, v23, vcc
	v_cmp_le_i32_e32 vcc, v171, v0
	v_max3_f32 v18, v18, v96, v97
	s_nop 0
	v_cndmask_b32_e32 v98, v236, v24, vcc
	v_cmp_le_i32_e32 vcc, v172, v0
	s_nop 1
	v_cndmask_b32_e32 v99, v236, v25, vcc
	v_cmp_le_i32_e32 vcc, v173, v0
	v_max3_f32 v18, v18, v98, v99
	s_nop 0
	v_cndmask_b32_e32 v100, v236, v26, vcc
	v_cmp_le_i32_e32 vcc, v174, v0
	s_nop 1
	v_cndmask_b32_e32 v101, v236, v27, vcc
	v_cmp_le_i32_e32 vcc, v175, v0
	v_max3_f32 v18, v18, v100, v101
	s_nop 0
	v_cndmask_b32_e32 v102, v236, v28, vcc
	v_cmp_le_i32_e32 vcc, v176, v0
	s_nop 1
	v_cndmask_b32_e32 v103, v236, v29, vcc
	v_cmp_le_i32_e32 vcc, v177, v0
	v_max3_f32 v18, v18, v102, v103
	s_nop 0
	v_cndmask_b32_e32 v104, v236, v30, vcc
	v_cmp_le_i32_e32 vcc, v178, v0
	s_nop 1
	v_cndmask_b32_e32 v105, v236, v31, vcc
	v_cmp_le_i32_e32 vcc, v179, v0
	v_max3_f32 v18, v18, v104, v105
	s_nop 0
	v_cndmask_b32_e32 v106, v236, v32, vcc
	v_cmp_le_i32_e32 vcc, v180, v0
	s_nop 1
	v_cndmask_b32_e32 v107, v236, v33, vcc
	v_cmp_le_i32_e32 vcc, v181, v0
	v_max3_f32 v18, v18, v106, v107
	s_nop 0
	v_cndmask_b32_e32 v108, v236, v2, vcc
	v_cmp_lt_i32_e32 vcc, v181, v0
	s_nop 1
	v_cndmask_b32_e32 v109, v236, v3, vcc
	v_cmp_le_i32_e32 vcc, v182, v0
	v_max3_f32 v2, v18, v108, v109
	s_nop 0
	v_cndmask_b32_e32 v110, v236, v4, vcc
	v_cmp_le_i32_e32 vcc, v183, v0
	s_nop 1
	v_cndmask_b32_e32 v111, v236, v5, vcc
	v_cmp_le_i32_e32 vcc, v184, v0
	v_max3_f32 v2, v2, v110, v111
	s_nop 0
	v_cndmask_b32_e32 v129, v236, v6, vcc
	v_cmp_le_i32_e32 vcc, v185, v0
	s_nop 1
	v_cndmask_b32_e32 v130, v236, v7, vcc
	v_cmp_le_i32_e32 vcc, v186, v0
	v_max3_f32 v2, v2, v129, v130
	s_nop 0
	v_cndmask_b32_e32 v56, v236, v8, vcc
	v_cmp_le_i32_e32 vcc, v187, v0
	s_nop 1
	v_cndmask_b32_e32 v57, v236, v9, vcc
	v_cmp_le_i32_e32 vcc, v188, v0
	v_max3_f32 v2, v2, v56, v57
	s_nop 0
	v_cndmask_b32_e32 v58, v236, v10, vcc
	v_cmp_le_i32_e32 vcc, v189, v0
	s_nop 1
	v_cndmask_b32_e32 v59, v236, v11, vcc
	v_cmp_le_i32_e32 vcc, v190, v0
	v_max3_f32 v2, v2, v58, v59
	s_nop 0
	v_cndmask_b32_e32 v62, v236, v12, vcc
	v_cmp_le_i32_e32 vcc, v191, v0
	s_nop 1
	v_cndmask_b32_e32 v63, v236, v13, vcc
	v_cmp_le_i32_e32 vcc, v192, v0
	v_max3_f32 v2, v2, v62, v63
	s_nop 0
	v_cndmask_b32_e32 v65, v236, v14, vcc
	v_cmp_le_i32_e32 vcc, v193, v0
	s_nop 1
	v_cndmask_b32_e32 v64, v236, v15, vcc
	v_cmp_le_i32_e32 vcc, v194, v0
	v_max3_f32 v2, v2, v65, v64
	s_nop 0
	v_cndmask_b32_e32 v61, v236, v16, vcc
	v_cmp_le_i32_e32 vcc, v195, v0
	s_nop 1
	v_cndmask_b32_e32 v0, v236, v17, vcc
	v_max3_f32 v2, v2, v61, v0
	ds_bpermute_b32 v3, v196, v2
	v_cmp_lt_u32_e32 vcc, 30, v243
	s_waitcnt lgkmcnt(0)
	v_max_f32_e32 v3, v3, v3
	v_max_f32_e32 v60, v2, v3
	v_sub_f32_e32 v2, v50, v60
	v_exp_f32_e32 v2, v2
	v_sub_f32_e32 v3, v51, v60
	v_exp_f32_e32 v3, v3
	v_sub_f32_e32 v13, v70, v60
	v_add_f32_e32 v4, 0, v2
	v_exp_f32_e32 v14, v13
	v_add_f32_e32 v5, v3, v4
	v_sub_f32_e32 v4, v52, v60
	v_exp_f32_e32 v4, v4
	v_sub_f32_e32 v13, v71, v60
	v_exp_f32_e32 v15, v13
	v_sub_f32_e32 v13, v72, v60
	v_add_f32_e32 v6, v4, v5
	v_sub_f32_e32 v5, v53, v60
	v_exp_f32_e32 v5, v5
	v_exp_f32_e32 v18, v13
	v_sub_f32_e32 v13, v73, v60
	v_exp_f32_e32 v19, v13
	v_add_f32_e32 v7, v5, v6
	v_sub_f32_e32 v6, v54, v60
	v_exp_f32_e32 v6, v6
	v_sub_f32_e32 v13, v74, v60
	v_exp_f32_e32 v20, v13
	v_sub_f32_e32 v13, v75, v60
	v_add_f32_e32 v8, v6, v7
	v_sub_f32_e32 v7, v55, v60
	v_exp_f32_e32 v7, v7
	v_exp_f32_e32 v21, v13
	v_sub_f32_e32 v29, v44, v60
	v_exp_f32_e32 v30, v29
	v_add_f32_e32 v9, v7, v8
	v_sub_f32_e32 v8, v67, v60
	v_exp_f32_e32 v8, v8
	v_sub_f32_e32 v29, v45, v60
	v_exp_f32_e32 v31, v29
	v_sub_f32_e32 v29, v46, v60
	v_add_f32_e32 v10, v8, v9
	v_sub_f32_e32 v9, v68, v60
	v_exp_f32_e32 v9, v9
	v_sub_f32_e32 v45, v102, v60
	v_exp_f32_e32 v46, v45
	v_sub_f32_e32 v45, v103, v60
	v_add_f32_e32 v11, v9, v10
	v_sub_f32_e32 v10, v66, v60
	v_exp_f32_e32 v10, v10
	v_sub_f32_e32 v56, v56, v60
	v_exp_f32_e32 v56, v56
	v_sub_f32_e32 v57, v57, v60
	v_add_f32_e32 v12, v10, v11
	v_sub_f32_e32 v11, v69, v60
	v_exp_f32_e32 v11, v11
	v_exp_f32_e32 v57, v57
	v_sub_f32_e32 v58, v58, v60
	v_exp_f32_e32 v58, v58
	v_add_f32_e32 v12, v11, v12
	v_add_f32_e32 v12, v14, v12
	v_add_f32_e32 v12, v15, v12
	v_add_f32_e32 v12, v18, v12
	v_add_f32_e32 v12, v19, v12
	v_add_f32_e32 v12, v20, v12
	v_add_f32_e32 v13, v21, v12
	v_sub_f32_e32 v12, v34, v60
	v_exp_f32_e32 v12, v12
	v_exp_f32_e32 v34, v29
	v_sub_f32_e32 v29, v47, v60
	v_exp_f32_e32 v47, v45
	v_add_f32_e32 v16, v12, v13
	v_sub_f32_e32 v13, v35, v60
	v_exp_f32_e32 v13, v13
	v_exp_f32_e32 v35, v29
	v_sub_f32_e32 v29, v48, v60
	v_sub_f32_e32 v45, v104, v60
	v_add_f32_e32 v17, v13, v16
	v_sub_f32_e32 v16, v36, v60
	v_exp_f32_e32 v16, v16
	v_exp_f32_e32 v36, v29
	v_sub_f32_e32 v29, v49, v60
	v_exp_f32_e32 v50, v45
	v_add_f32_e32 v22, v16, v17
	v_sub_f32_e32 v17, v37, v60
	v_exp_f32_e32 v17, v17
	v_exp_f32_e32 v37, v29
	v_sub_f32_e32 v45, v105, v60
	v_exp_f32_e32 v51, v45
	v_add_f32_e32 v23, v17, v22
	v_sub_f32_e32 v22, v38, v60
	v_exp_f32_e32 v22, v22
	v_sub_f32_e32 v45, v106, v60
	v_exp_f32_e32 v52, v45
	v_sub_f32_e32 v45, v107, v60
	v_add_f32_e32 v24, v22, v23
	v_sub_f32_e32 v23, v39, v60
	v_exp_f32_e32 v23, v23
	v_exp_f32_e32 v53, v45
	v_sub_f32_e32 v59, v59, v60
	v_exp_f32_e32 v59, v59
	v_add_f32_e32 v25, v23, v24
	v_sub_f32_e32 v24, v40, v60
	v_exp_f32_e32 v24, v24
	v_sub_f32_e32 v62, v62, v60
	v_exp_f32_e32 v62, v62
	v_sub_f32_e32 v63, v63, v60
	v_add_f32_e32 v26, v24, v25
	v_sub_f32_e32 v25, v41, v60
	v_exp_f32_e32 v25, v25
	v_exp_f32_e32 v63, v63
	v_sub_f32_e32 v65, v65, v60
	v_sub_f32_e32 v64, v64, v60
	v_add_f32_e32 v27, v25, v26
	v_sub_f32_e32 v26, v42, v60
	v_exp_f32_e32 v26, v26
	v_sub_f32_e32 v61, v61, v60
	v_sub_f32_e32 v0, v0, v60
	v_add_f32_e32 v28, v26, v27
	v_sub_f32_e32 v27, v43, v60
	v_exp_f32_e32 v27, v27
	s_nop 0
	v_add_f32_e32 v28, v27, v28
	v_add_f32_e32 v28, v30, v28
	v_add_f32_e32 v28, v31, v28
	v_add_f32_e32 v28, v34, v28
	v_add_f32_e32 v28, v35, v28
	v_add_f32_e32 v28, v36, v28
	v_add_f32_e32 v29, v37, v28
	v_sub_f32_e32 v28, v76, v60
	v_exp_f32_e32 v28, v28
	v_exp_f32_e32 v76, v65
	v_add_f32_e32 v32, v28, v29
	v_sub_f32_e32 v29, v77, v60
	v_exp_f32_e32 v29, v29
	v_exp_f32_e32 v77, v64
	v_add_f32_e32 v33, v29, v32
	v_sub_f32_e32 v32, v78, v60
	v_exp_f32_e32 v32, v32
	v_exp_f32_e32 v78, v61
	v_add_f32_e32 v38, v32, v33
	v_sub_f32_e32 v33, v79, v60
	v_exp_f32_e32 v33, v33
	v_exp_f32_e32 v79, v0
	v_mov_b32_e32 v0, v1
	v_add_f32_e32 v39, v33, v38
	v_sub_f32_e32 v38, v96, v60
	v_exp_f32_e32 v38, v38
	s_nop 0
	v_add_f32_e32 v40, v38, v39
	v_sub_f32_e32 v39, v97, v60
	v_exp_f32_e32 v39, v39
	s_nop 0
	v_add_f32_e32 v41, v39, v40
	v_sub_f32_e32 v40, v98, v60
	v_exp_f32_e32 v40, v40
	s_nop 0
	v_add_f32_e32 v42, v40, v41
	v_sub_f32_e32 v41, v99, v60
	v_exp_f32_e32 v41, v41
	s_nop 0
	v_add_f32_e32 v43, v41, v42
	v_sub_f32_e32 v42, v100, v60
	v_exp_f32_e32 v42, v42
	s_nop 0
	v_add_f32_e32 v44, v42, v43
	v_sub_f32_e32 v43, v101, v60
	v_exp_f32_e32 v43, v43
	s_nop 0
	v_add_f32_e32 v44, v43, v44
	v_add_f32_e32 v44, v46, v44
	v_add_f32_e32 v44, v47, v44
	v_add_f32_e32 v44, v50, v44
	v_add_f32_e32 v44, v51, v44
	v_add_f32_e32 v44, v52, v44
	v_add_f32_e32 v45, v53, v44
	v_sub_f32_e32 v44, v108, v60
	v_exp_f32_e32 v44, v44
	s_nop 0
	v_add_f32_e32 v48, v44, v45
	v_sub_f32_e32 v45, v109, v60
	v_exp_f32_e32 v45, v45
	s_nop 0
	v_add_f32_e32 v49, v45, v48
	v_sub_f32_e32 v48, v110, v60
	v_exp_f32_e32 v48, v48
	s_nop 0
	v_add_f32_e32 v54, v48, v49
	v_sub_f32_e32 v49, v111, v60
	v_exp_f32_e32 v49, v49
	s_nop 0
	v_add_f32_e32 v55, v49, v54
	v_sub_f32_e32 v54, v129, v60
	v_exp_f32_e32 v54, v54
	s_nop 0
	v_add_f32_e32 v66, v54, v55
	v_sub_f32_e32 v55, v130, v60
	v_exp_f32_e32 v55, v55
	s_nop 0
	v_add_f32_e32 v66, v55, v66
	v_add_f32_e32 v66, v56, v66
	v_add_f32_e32 v66, v57, v66
	v_add_f32_e32 v66, v58, v66
	v_add_f32_e32 v66, v59, v66
	v_add_f32_e32 v66, v62, v66
	v_add_f32_e32 v66, v63, v66
	v_add_f32_e32 v65, v76, v66
	v_add_f32_e32 v64, v77, v65
	v_add_f32_e32 v61, v78, v64
	v_add_f32_e32 v60, v79, v61
	ds_bpermute_b32 v61, v196, v60
	s_and_saveexec_b64 s[0:1], vcc
	s_cbranch_execz .LBB0_946
	s_waitcnt lgkmcnt(0)
	v_add_f32_e32 v0, v60, v61
	v_div_scale_f32 v60, s[26:27], v0, v0, 1.0
	v_rcp_f32_e32 v61, v60
	v_div_scale_f32 v64, vcc, 1.0, v0, 1.0
	v_fma_f32 v65, -v60, v61, 1.0
	v_fmac_f32_e32 v61, v65, v61
	v_mul_f32_e32 v65, v64, v61
	v_fma_f32 v66, -v60, v65, v64
	v_fmac_f32_e32 v65, v66, v61
	v_fma_f32 v60, -v60, v65, v64
	v_div_fmas_f32 v60, v60, v61, v65
	v_div_fixup_f32 v0, v60, v0, 1.0
